# phase-0 weight conversion: the zero-padded w_in tiles issue their four row loads together
# baseline (speedup 1.0000x reference)
; DI void conv_tile(const float* __restrict__ src, int N, u16* __restrict__ dst, int ldd, int k0, int n0, int mode,
;                   const float* __restrict__ kscale, float* tl) {
;   const int t = get_tid();
;   const int r = t >> 4, c4 = (t & 15) * 4;
; #pragma unroll
;   for (int i = 0; i < 4; ++i) {
;     const int k = r + 16 * i;
;     float4 v = make_float4(0.f, 0.f, 0.f, 0.f);
;     if (n0 + c4 < N) v = *(const float4*)(src + (size_t)(k0 + k) * N + n0 + c4);
;     if (kscale) { const float s = kscale[k0 + k]; v.x *= s; v.y *= s; v.z *= s; v.w *= s; }
;     float* q = tl + k * 65 + c4;
;     q[0] = v.x; q[1] = v.y; q[2] = v.z; q[3] = v.w;
;   }
;   __syncthreads();
;   const int n = t >> 2, ks = (t & 3) * 16;
;   unsigned w[8];
; #pragma unroll
;   for (int j = 0; j < 8; ++j) w[j] = pack2(tl[(ks + 2 * j) * 65 + n], tl[(ks + 2 * j + 1) * 65 + n]);
;   const int nn = n0 + n;
;   const int drow = mode == 0 ? nn : ((nn >> 5) * 64 + (nn & 31) + (mode == 2 ? 32 : 0));
;   uint4* d = (uint4*)(dst + (size_t)drow * ldd + k0 + ks);
;   d[0] = make_uint4(w[0], w[1], w[2], w[3]);
;   d[1] = make_uint4(w[4], w[5], w[6], w[7]);
;   __syncthreads();
.LBB0_59:
	s_and_b32 s8, s24, 0xffff
	s_mul_i32 s8, s8, 0xba2f
	s_lshr_b32 s9, s8, 21
	s_mul_i32 s9, s9, 44
	s_lshr_b32 s8, s8, 15
	s_sub_i32 s36, s24, s9
	s_load_dwordx16 s[76:91], s[0:1], 0x40
	s_and_b32 s22, s8, 0xffc0
	s_and_b32 s37, s36, 0xffff
	s_cmp_lt_u32 s37, 43
	v_mov_b32_e32 v10, v132
	s_cselect_b64 s[24:25], -1, 0
	s_lshl_b32 s8, s36, 8
	s_and_b32 s8, s8, 0x3ff00
	v_lshlrev_b32_e32 v0, 2, v10
	v_and_b32_e32 v1, 60, v0
	s_waitcnt lgkmcnt(0)
	s_add_u32 s8, s80, s8
	s_addc_u32 s9, s81, 0
	v_lshlrev_b32_e32 v8, 2, v1
	v_ashrrev_i32_e32 v11, 4, v10
	s_cmp_gt_u32 s37, 42
	v_lshl_add_u64 v[6:7], s[8:9], 0, v[8:9]
	v_mov_b32_e32 v0, 0
	v_mov_b32_e32 v2, 0
	v_mov_b32_e32 v3, 0
	v_mov_b32_e32 v4, 0
	v_mov_b32_e32 v5, 0
	v_mov_b32_e32 v224, 0
	v_mov_b32_e32 v225, 0
	v_mov_b32_e32 v226, 0
	v_mov_b32_e32 v227, 0
	v_mov_b32_e32 v228, 0
	v_mov_b32_e32 v229, 0
	v_mov_b32_e32 v230, 0
	v_mov_b32_e32 v231, 0
	v_mov_b32_e32 v232, 0
	v_mov_b32_e32 v233, 0
	v_mov_b32_e32 v234, 0
	v_mov_b32_e32 v235, 0
	s_cbranch_scc1 .LBB0_61
	v_add_u32_e32 v2, s22, v11
	v_mad_i64_i32 v[2:3], s[8:9], v2, s30, v[6:7]
	global_load_dwordx4 v[2:5], v[2:3], off
	v_add3_u32 v236, v11, s22, 16
	v_mad_i64_i32 v[236:237], s[100:101], v236, s30, v[6:7]
	global_load_dwordx4 v[224:227], v[236:237], off
	v_add3_u32 v236, v11, s22, 32
	v_mad_i64_i32 v[236:237], s[100:101], v236, s30, v[6:7]
	global_load_dwordx4 v[228:231], v[236:237], off
	v_add3_u32 v236, v11, s22, 48
	v_mad_i64_i32 v[236:237], s[100:101], v236, s30, v[6:7]
	global_load_dwordx4 v[232:235], v[236:237], off
.LBB0_61:
	v_lshl_add_u32 v1, v1, 2, 0
	v_mul_lo_u32 v8, v11, s27
	v_add_u32_e32 v8, v1, v8
	v_cndmask_b32_e64 v1, 0, 1, s[24:25]
	s_waitcnt vmcnt(3)
	ds_write2_b32 v8, v2, v3 offset1:1
	ds_write2_b32 v8, v4, v5 offset0:2 offset1:3
	v_cmp_ne_u32_e64 s[8:9], 1, v1
	s_andn2_b64 vcc, exec, s[24:25]
.LBB0_63:
	v_add_u32_e32 v4, 0x1040, v8
	s_waitcnt vmcnt(2)
	ds_write2_b32 v4, v224, v225 offset1:1
	v_add_u32_e32 v0, 0x1048, v8
	ds_write2_b32 v0, v226, v227 offset1:1
.LBB0_65:
	v_add_u32_e32 v1, 0x2080, v8
	s_waitcnt vmcnt(1)
	ds_write2_b32 v1, v228, v229 offset1:1
	v_add_u32_e32 v1, 0x2088, v8
	ds_write2_b32 v1, v230, v231 offset1:1
.LBB0_67:
	v_add_u32_e32 v4, 0x30c0, v8
	s_waitcnt vmcnt(0)
	ds_write2_b32 v4, v232, v233 offset1:1
	v_add_u32_e32 v0, 0x30c8, v8
	ds_write2_b32 v0, v234, v235 offset1:1
	v_lshlrev_b32_e32 v0, 4, v10
	v_and_b32_e32 v8, 48, v0
	v_mul_u32_u24_e32 v0, 0x41, v8
	v_and_b32_e32 v2, -4, v10
	v_lshlrev_b32_e32 v3, 2, v0
	v_add3_u32 v12, 0, v2, v3
	v_add3_u32 v14, 0, v3, v2
	s_waitcnt lgkmcnt(0)
	s_barrier
	ds_read2_b32 v[0:1], v12 offset1:130
	ds_read2_b32 v[2:3], v14 offset0:65 offset1:195
	v_ashrrev_i32_e32 v16, 2, v10
	v_add_u32_e32 v4, 0x400, v14
	v_add_u32_e32 v6, 0x800, v12
	v_add_u32_e32 v10, 0x800, v14
	s_waitcnt lgkmcnt(0)
	v_cvt_pk_bf16_f32 v0, v0, v2
	v_add_u32_e32 v2, 0x400, v12
	v_cvt_pk_bf16_f32 v1, v1, v3
	ds_read2_b32 v[2:3], v2 offset0:4 offset1:134
	ds_read2_b32 v[4:5], v4 offset0:69 offset1:199
	ds_read2_b32 v[6:7], v6 offset0:8 offset1:138
	ds_read2_b32 v[10:11], v10 offset0:73 offset1:203
	s_lshl_b32 s8, s36, 6
	s_and_b32 s8, 0xffff, s8
	v_add_u32_e32 v12, 0xc00, v12
	v_add_u32_e32 v14, 0xc00, v14
	s_waitcnt lgkmcnt(2)
	v_cvt_pk_bf16_f32 v2, v2, v4
	s_waitcnt lgkmcnt(0)
	v_cvt_pk_bf16_f32 v4, v6, v10
	v_add_u32_e32 v10, s8, v16
	ds_read2_b32 v[12:13], v12 offset0:12 offset1:142
	ds_read2_b32 v[14:15], v14 offset0:77 offset1:207
	v_cvt_pk_bf16_f32 v3, v3, v5
	v_cvt_pk_bf16_f32 v5, v7, v11
	v_ashrrev_i32_e32 v11, 31, v10
	v_lshlrev_b64 v[10:11], 11, v[10:11]
	s_load_dwordx16 s[36:51], s[0:1], 0x0
	v_lshl_add_u64 v[10:11], s[18:19], 0, v[10:11]
	s_lshl_b32 s22, s22, 1
	v_lshl_add_u64 v[10:11], v[10:11], 0, s[22:23]
	v_lshlrev_b32_e32 v8, 1, v8
	v_lshl_add_u64 v[10:11], v[10:11], 0, v[8:9]
	s_waitcnt lgkmcnt(0)
	v_cvt_pk_bf16_f32 v6, v12, v14
	v_cvt_pk_bf16_f32 v7, v13, v15
	global_store_dwordx4 v[10:11], v[0:3], off
	global_store_dwordx4 v[10:11], v[4:7], off offset:16
	s_barrier
